# v42 + attention unit output epilogue: per-wave LDS transpose and 8 sixteen-byte stores per lane instead of 64 two-byte stores
# speedup vs baseline: 1.0108x; 1.0017x over previous
; __device__ __forceinline__ int crow(int r, int hi) { return (r & 3) + 8 * (r >> 2) + 4 * hi; }
; __device__ __forceinline__ unsigned cvtpk(float lo, float hi) { unsigned r; asm volatile("v_cvt_pk_bf16_f32 %0, %1, %2" : "=v"(r) : "v"(lo), "v"(hi)); return r; }
; __device__ __forceinline__ void attn_unit(const bf16_t* __restrict__ Qb, const bf16_t* __restrict__ KV, const bf16_t* __restrict__ KP, bf16_t* __restrict__ Ob, ...
;     ...
;   if (hi == 0) li_l[r32] = l_reg; asm volatile("s_waitcnt lgkmcnt(0)" ::: "memory");
;   float rli[16];
; #pragma unroll
;   for (int r = 0; r < 16; ++r) rli[r] = __builtin_amdgcn_rcpf(li_l[crow(r, hi)]);
;   bf16_t* Ow = Ob + (size_t)(qrow0 + wid * QBLK) * LDO + h * VD;
; #pragma unroll
;   for (int r = 0; r < 16; ++r) { const int orow = crow(r, hi);
; #pragma unroll
;     for (int d0 = 0; d0 < 4; ++d0) { const float v = o[d0][r] * rli[r]; Ow[(size_t)orow * LDO + d0 * 32 + r32] = (bf16_t)(cvtpk(v, v) & 0xffffu); } }
.LBB0_1451:
	s_or_b64 exec, exec, s[8:9]
	s_waitcnt lgkmcnt(0)
	v_add_u32_e32 v72, v179, v172
	ds_read_b128 v[64:67], v72
	ds_read_b128 v[68:71], v72 offset:32
	ds_read_b128 v[76:79], v72 offset:64
	ds_read_b128 v[80:83], v72 offset:96
	s_mul_i32 s44, s40, 8704
	s_lshl_b32 s45, s3, 8
	v_mul_u32_u24_e32 v73, 1088, v185
	v_lshl_add_u32 v73, v184, 1, v73
	v_add_u32_e32 v73, s44, v73
	v_and_b32_e32 v74, 63, v188
	v_lshrrev_b32_e32 v84, 4, v74
	v_and_b32_e32 v85, 15, v74
	v_mul_u32_u24_e32 v75, 272, v84
	v_lshl_add_u32 v75, v85, 4, v75
	v_add_u32_e32 v75, s44, v75
	v_add_u32_e32 v84, v178, v84
	v_lshlrev_b32_e32 v84, 11, v84
	v_lshl_add_u32 v84, v85, 4, v84
	v_add_u32_e32 v84, s45, v84
	s_waitcnt lgkmcnt(0)
	v_rcp_f32_e32 v64, v64
	v_rcp_f32_e32 v65, v65
	v_rcp_f32_e32 v66, v66
	v_rcp_f32_e32 v67, v67
	v_rcp_f32_e32 v68, v68
	v_rcp_f32_e32 v69, v69
	v_rcp_f32_e32 v70, v70
	v_rcp_f32_e32 v71, v71
	v_rcp_f32_e32 v76, v76
	v_rcp_f32_e32 v77, v77
	v_rcp_f32_e32 v78, v78
	v_rcp_f32_e32 v79, v79
	v_rcp_f32_e32 v80, v80
	v_rcp_f32_e32 v81, v81
	v_rcp_f32_e32 v82, v82
	v_rcp_f32_e32 v83, v83
	s_nop 1
	v_mul_f32_e32 v86, v0, v64
	v_cvt_pk_bf16_f32 v86, v86, v86
	ds_write_b16 v73, v86 offset:0
	v_mul_f32_e32 v87, v48, v64
	v_cvt_pk_bf16_f32 v87, v87, v87
	ds_write_b16 v73, v87 offset:64
	v_mul_f32_e32 v88, v32, v64
	v_cvt_pk_bf16_f32 v88, v88, v88
	ds_write_b16 v73, v88 offset:128
	v_mul_f32_e32 v89, v16, v64
	v_cvt_pk_bf16_f32 v89, v89, v89
	ds_write_b16 v73, v89 offset:192
	v_mul_f32_e32 v86, v1, v65
	v_cvt_pk_bf16_f32 v86, v86, v86
	ds_write_b16 v73, v86 offset:272
	v_mul_f32_e32 v87, v49, v65
	v_cvt_pk_bf16_f32 v87, v87, v87
	ds_write_b16 v73, v87 offset:336
	v_mul_f32_e32 v88, v33, v65
	v_cvt_pk_bf16_f32 v88, v88, v88
	ds_write_b16 v73, v88 offset:400
	v_mul_f32_e32 v89, v17, v65
	v_cvt_pk_bf16_f32 v89, v89, v89
	ds_write_b16 v73, v89 offset:464
	v_mul_f32_e32 v86, v2, v66
	v_cvt_pk_bf16_f32 v86, v86, v86
	ds_write_b16 v73, v86 offset:544
	v_mul_f32_e32 v87, v50, v66
	v_cvt_pk_bf16_f32 v87, v87, v87
	ds_write_b16 v73, v87 offset:608
	v_mul_f32_e32 v88, v34, v66
	v_cvt_pk_bf16_f32 v88, v88, v88
	ds_write_b16 v73, v88 offset:672
	v_mul_f32_e32 v89, v18, v66
	v_cvt_pk_bf16_f32 v89, v89, v89
	ds_write_b16 v73, v89 offset:736
	v_mul_f32_e32 v86, v3, v67
	v_cvt_pk_bf16_f32 v86, v86, v86
	ds_write_b16 v73, v86 offset:816
	v_mul_f32_e32 v87, v51, v67
	v_cvt_pk_bf16_f32 v87, v87, v87
	ds_write_b16 v73, v87 offset:880
	v_mul_f32_e32 v88, v35, v67
	v_cvt_pk_bf16_f32 v88, v88, v88
	ds_write_b16 v73, v88 offset:944
	v_mul_f32_e32 v89, v19, v67
	v_cvt_pk_bf16_f32 v89, v89, v89
	ds_write_b16 v73, v89 offset:1008
	v_mul_f32_e32 v86, v4, v68
	v_cvt_pk_bf16_f32 v86, v86, v86
	ds_write_b16 v73, v86 offset:2176
	v_mul_f32_e32 v87, v52, v68
	v_cvt_pk_bf16_f32 v87, v87, v87
	ds_write_b16 v73, v87 offset:2240
	v_mul_f32_e32 v88, v36, v68
	v_cvt_pk_bf16_f32 v88, v88, v88
	ds_write_b16 v73, v88 offset:2304
	v_mul_f32_e32 v89, v20, v68
	v_cvt_pk_bf16_f32 v89, v89, v89
	ds_write_b16 v73, v89 offset:2368
	v_mul_f32_e32 v86, v5, v69
	v_cvt_pk_bf16_f32 v86, v86, v86
	ds_write_b16 v73, v86 offset:2448
	v_mul_f32_e32 v87, v53, v69
	v_cvt_pk_bf16_f32 v87, v87, v87
	ds_write_b16 v73, v87 offset:2512
	v_mul_f32_e32 v88, v37, v69
	v_cvt_pk_bf16_f32 v88, v88, v88
	ds_write_b16 v73, v88 offset:2576
	v_mul_f32_e32 v89, v21, v69
	v_cvt_pk_bf16_f32 v89, v89, v89
	ds_write_b16 v73, v89 offset:2640
	v_mul_f32_e32 v86, v6, v70
	v_cvt_pk_bf16_f32 v86, v86, v86
	ds_write_b16 v73, v86 offset:2720
	v_mul_f32_e32 v87, v54, v70
	v_cvt_pk_bf16_f32 v87, v87, v87
	ds_write_b16 v73, v87 offset:2784
	v_mul_f32_e32 v88, v38, v70
	v_cvt_pk_bf16_f32 v88, v88, v88
	ds_write_b16 v73, v88 offset:2848
	v_mul_f32_e32 v89, v22, v70
	v_cvt_pk_bf16_f32 v89, v89, v89
	ds_write_b16 v73, v89 offset:2912
	v_mul_f32_e32 v86, v7, v71
	v_cvt_pk_bf16_f32 v86, v86, v86
	ds_write_b16 v73, v86 offset:2992
	v_mul_f32_e32 v87, v55, v71
	v_cvt_pk_bf16_f32 v87, v87, v87
	ds_write_b16 v73, v87 offset:3056
	v_mul_f32_e32 v88, v39, v71
	v_cvt_pk_bf16_f32 v88, v88, v88
	ds_write_b16 v73, v88 offset:3120
	v_mul_f32_e32 v89, v23, v71
	v_cvt_pk_bf16_f32 v89, v89, v89
	ds_write_b16 v73, v89 offset:3184
	v_mul_f32_e32 v86, v8, v76
	v_cvt_pk_bf16_f32 v86, v86, v86
	ds_write_b16 v73, v86 offset:4352
; __device__ __forceinline__ int crow(int r, int hi) { return (r & 3) + 8 * (r >> 2) + 4 * hi; }
; __device__ __forceinline__ unsigned cvtpk(float lo, float hi) { unsigned r; asm volatile("v_cvt_pk_bf16_f32 %0, %1, %2" : "=v"(r) : "v"(lo), "v"(hi)); return r; }
; __device__ __forceinline__ void attn_unit(const bf16_t* __restrict__ Qb, const bf16_t* __restrict__ KV, const bf16_t* __restrict__ KP, bf16_t* __restrict__ Ob, ...
;     ...
;   if (hi == 0) li_l[r32] = l_reg; asm volatile("s_waitcnt lgkmcnt(0)" ::: "memory");
;   float rli[16];
; #pragma unroll
;   for (int r = 0; r < 16; ++r) rli[r] = __builtin_amdgcn_rcpf(li_l[crow(r, hi)]);
;   bf16_t* Ow = Ob + (size_t)(qrow0 + wid * QBLK) * LDO + h * VD;
; #pragma unroll
;   for (int r = 0; r < 16; ++r) { const int orow = crow(r, hi);
; #pragma unroll
;     for (int d0 = 0; d0 < 4; ++d0) { const float v = o[d0][r] * rli[r]; Ow[(size_t)orow * LDO + d0 * 32 + r32] = (bf16_t)(cvtpk(v, v) & 0xffffu); } }
;   __syncthreads();
	v_mul_f32_e32 v87, v56, v76
	v_cvt_pk_bf16_f32 v87, v87, v87
	ds_write_b16 v73, v87 offset:4416
	v_mul_f32_e32 v88, v40, v76
	v_cvt_pk_bf16_f32 v88, v88, v88
	ds_write_b16 v73, v88 offset:4480
	v_mul_f32_e32 v89, v24, v76
	v_cvt_pk_bf16_f32 v89, v89, v89
	ds_write_b16 v73, v89 offset:4544
	v_mul_f32_e32 v86, v9, v77
	v_cvt_pk_bf16_f32 v86, v86, v86
	ds_write_b16 v73, v86 offset:4624
	v_mul_f32_e32 v87, v57, v77
	v_cvt_pk_bf16_f32 v87, v87, v87
	ds_write_b16 v73, v87 offset:4688
	v_mul_f32_e32 v88, v41, v77
	v_cvt_pk_bf16_f32 v88, v88, v88
	ds_write_b16 v73, v88 offset:4752
	v_mul_f32_e32 v89, v25, v77
	v_cvt_pk_bf16_f32 v89, v89, v89
	ds_write_b16 v73, v89 offset:4816
	v_mul_f32_e32 v86, v10, v78
	v_cvt_pk_bf16_f32 v86, v86, v86
	ds_write_b16 v73, v86 offset:4896
	v_mul_f32_e32 v87, v58, v78
	v_cvt_pk_bf16_f32 v87, v87, v87
	ds_write_b16 v73, v87 offset:4960
	v_mul_f32_e32 v88, v42, v78
	v_cvt_pk_bf16_f32 v88, v88, v88
	ds_write_b16 v73, v88 offset:5024
	v_mul_f32_e32 v89, v26, v78
	v_cvt_pk_bf16_f32 v89, v89, v89
	ds_write_b16 v73, v89 offset:5088
	v_mul_f32_e32 v86, v11, v79
	v_cvt_pk_bf16_f32 v86, v86, v86
	ds_write_b16 v73, v86 offset:5168
	v_mul_f32_e32 v87, v59, v79
	v_cvt_pk_bf16_f32 v87, v87, v87
	ds_write_b16 v73, v87 offset:5232
	v_mul_f32_e32 v88, v43, v79
	v_cvt_pk_bf16_f32 v88, v88, v88
	ds_write_b16 v73, v88 offset:5296
	v_mul_f32_e32 v89, v27, v79
	v_cvt_pk_bf16_f32 v89, v89, v89
	ds_write_b16 v73, v89 offset:5360
	v_mul_f32_e32 v86, v12, v80
	v_cvt_pk_bf16_f32 v86, v86, v86
	ds_write_b16 v73, v86 offset:6528
	v_mul_f32_e32 v87, v60, v80
	v_cvt_pk_bf16_f32 v87, v87, v87
	ds_write_b16 v73, v87 offset:6592
	v_mul_f32_e32 v88, v44, v80
	v_cvt_pk_bf16_f32 v88, v88, v88
	ds_write_b16 v73, v88 offset:6656
	v_mul_f32_e32 v89, v28, v80
	v_cvt_pk_bf16_f32 v89, v89, v89
	ds_write_b16 v73, v89 offset:6720
	v_mul_f32_e32 v86, v13, v81
	v_cvt_pk_bf16_f32 v86, v86, v86
	ds_write_b16 v73, v86 offset:6800
	v_mul_f32_e32 v87, v61, v81
	v_cvt_pk_bf16_f32 v87, v87, v87
	ds_write_b16 v73, v87 offset:6864
	v_mul_f32_e32 v88, v45, v81
	v_cvt_pk_bf16_f32 v88, v88, v88
	ds_write_b16 v73, v88 offset:6928
	v_mul_f32_e32 v89, v29, v81
	v_cvt_pk_bf16_f32 v89, v89, v89
	ds_write_b16 v73, v89 offset:6992
	v_mul_f32_e32 v86, v14, v82
	v_cvt_pk_bf16_f32 v86, v86, v86
	ds_write_b16 v73, v86 offset:7072
	v_mul_f32_e32 v87, v62, v82
	v_cvt_pk_bf16_f32 v87, v87, v87
	ds_write_b16 v73, v87 offset:7136
	v_mul_f32_e32 v88, v46, v82
	v_cvt_pk_bf16_f32 v88, v88, v88
	ds_write_b16 v73, v88 offset:7200
	v_mul_f32_e32 v89, v30, v82
	v_cvt_pk_bf16_f32 v89, v89, v89
	ds_write_b16 v73, v89 offset:7264
	v_mul_f32_e32 v86, v15, v83
	v_cvt_pk_bf16_f32 v86, v86, v86
	ds_write_b16 v73, v86 offset:7344
	v_mul_f32_e32 v87, v63, v83
	v_cvt_pk_bf16_f32 v87, v87, v87
	ds_write_b16 v73, v87 offset:7408
	v_mul_f32_e32 v88, v47, v83
	v_cvt_pk_bf16_f32 v88, v88, v88
	ds_write_b16 v73, v88 offset:7472
	v_mul_f32_e32 v89, v31, v83
	v_cvt_pk_bf16_f32 v89, v89, v89
	ds_write_b16 v73, v89 offset:7536
	s_waitcnt lgkmcnt(0)
	ds_read_b128 v[96:99], v75 offset:0
	ds_read_b128 v[100:103], v75 offset:1088
	ds_read_b128 v[104:107], v75 offset:2176
	ds_read_b128 v[108:111], v75 offset:3264
	ds_read_b128 v[112:115], v75 offset:4352
	ds_read_b128 v[116:119], v75 offset:5440
	ds_read_b128 v[120:123], v75 offset:6528
	ds_read_b128 v[124:127], v75 offset:7616
	s_waitcnt lgkmcnt(7)
	global_store_dwordx4 v84, v[96:99], s[16:17]
	s_waitcnt lgkmcnt(6)
	v_add_u32_e32 v84, 0x2000, v84
	global_store_dwordx4 v84, v[100:103], s[16:17]
	s_waitcnt lgkmcnt(5)
	v_add_u32_e32 v84, 0x2000, v84
	global_store_dwordx4 v84, v[104:107], s[16:17]
	s_waitcnt lgkmcnt(4)
	v_add_u32_e32 v84, 0x2000, v84
	global_store_dwordx4 v84, v[108:111], s[16:17]
	s_waitcnt lgkmcnt(3)
	v_add_u32_e32 v84, 0x2000, v84
	global_store_dwordx4 v84, v[112:115], s[16:17]
	s_waitcnt lgkmcnt(2)
	v_add_u32_e32 v84, 0x2000, v84
	global_store_dwordx4 v84, v[116:119], s[16:17]
	s_waitcnt lgkmcnt(1)
	v_add_u32_e32 v84, 0x2000, v84
	global_store_dwordx4 v84, v[120:123], s[16:17]
	s_waitcnt lgkmcnt(0)
	v_add_u32_e32 v84, 0x2000, v84
	global_store_dwordx4 v84, v[124:127], s[16:17]
	s_add_i32 s2, s2, s1
	s_cmpk_gt_i32 s2, 0x1ff
	s_waitcnt vmcnt(63) expcnt(7) lgkmcnt(15)
	s_barrier
	s_cbranch_scc1 .LBB0_1469
